# gate phase: all sixteen operand loads of the q.mean(k) product requested up front (on hand-written phase 0)
# speedup vs baseline: 1.0080x; 1.0061x over previous
; __device__ __forceinline__ void moba_gate_phase(Frame& F, const bf16* qkvg, const bf16* kmb, int* cntg, unsigned short* listg, unsigned char* selvg) {
;     ...
;         { const bf16* qp = qkvg + (size_t)(j * 256 + F.wave * 32 + r) * 16384 + h * 128 + h2 * 8; const bf16* kp = kmb + ((size_t)h * MOBA_NB + r) * 128 + h2 * 8;
;           f32x16 gs = zero16();
; #pragma unroll
;           for (int ks = 0; ks < 8; ++ks) { const bf16x8 a = *(const bf16x8*)(kp + ks * 16), b = *(const bf16x8*)(qp + ks * 16); gs = __builtin_amdgcn_mfma_f32_32x32x16_bf16(a, b, gs, 0, 0, 0); }
;           float v0 = -INFINITY, v1 = -INFINITY, v2 = -INFINITY;
; #pragma unroll
;           for (int n = 0; n < 32; ++n) { const int ri = (n & 3) + 4 * (n >> 3); const float own = gs[ri], oth = other_half(own, h2 != 0);
;               float s = (((n >> 2) & 1) == h2) ? own : oth; if (n >= j) s = -INFINITY;
;               if (s > v0) { v2 = v1; s2 = s1; v1 = v0; s1 = s0; v0 = s; s0 = n; } else if (s > v1) { v2 = v1; s2 = s1; v1 = s; s1 = n; } else if (s > v2) { v2 = s; s2 = n; } }
.LBB0_1343:
	s_and_b32 s34, s52, 31
	s_lshl_b32 s53, s34, 8
	s_ashr_i32 s42, s52, 5
	s_add_i32 s53, s53, s33
	v_or_b32_e32 v36, s53, v34
	s_ashr_i32 s43, s42, 31
	v_lshlrev_b64 v[18:19], 15, v[36:37]
	s_lshl_b64 s[44:45], s[42:43], 5
	v_lshl_add_u64 v[56:57], s[26:27], 0, v[18:19]
	v_mov_b32_e32 v19, s45
	v_or_b32_e32 v18, s44, v34
	v_lshlrev_b64 v[18:19], 8, v[18:19]
	v_lshl_add_u64 v[72:73], v[38:39], 0, v[18:19]
	v_mov_b64_e32 v[32:33], v[16:17]
	v_mov_b64_e32 v[30:31], v[14:15]
	v_mov_b64_e32 v[28:29], v[12:13]
	v_mov_b64_e32 v[26:27], v[10:11]
	v_mov_b64_e32 v[24:25], v[8:9]
	v_mov_b64_e32 v[22:23], v[6:7]
	v_mov_b64_e32 v[20:21], v[4:5]
	v_mov_b64_e32 v[18:19], v[2:3]
	s_lshl_b32 s18, s42, 7
	s_ashr_i32 s19, s18, 31
	v_lshl_add_u64 v[56:57], s[18:19], 1, v[56:57]
	v_lshl_add_u64 v[74:75], v[56:57], 0, v[44:45]
	global_load_dwordx4 v[76:79], v[72:73], off
	global_load_dwordx4 v[108:111], v[74:75], off
	global_load_dwordx4 v[80:83], v[72:73], off offset:32
	global_load_dwordx4 v[112:115], v[74:75], off offset:32
	global_load_dwordx4 v[84:87], v[72:73], off offset:64
	global_load_dwordx4 v[116:119], v[74:75], off offset:64
	global_load_dwordx4 v[88:91], v[72:73], off offset:96
	global_load_dwordx4 v[120:123], v[74:75], off offset:96
	global_load_dwordx4 v[92:95], v[72:73], off offset:128
	global_load_dwordx4 v[124:127], v[74:75], off offset:128
	global_load_dwordx4 v[96:99], v[72:73], off offset:160
	global_load_dwordx4 v[128:131], v[74:75], off offset:160
	global_load_dwordx4 v[100:103], v[72:73], off offset:192
	global_load_dwordx4 v[132:135], v[74:75], off offset:192
	global_load_dwordx4 v[104:107], v[72:73], off offset:224
	global_load_dwordx4 v[136:139], v[74:75], off offset:224
	s_cmp_lg_u32 s34, 0
	s_cselect_b64 s[18:19], -1, 0
	s_cmp_gt_u32 s34, 1
	s_waitcnt vmcnt(14)
	v_mfma_f32_32x32x16_bf16 v[18:33], v[76:79], v[108:111], v[18:33]
	s_waitcnt vmcnt(12)
	v_mfma_f32_32x32x16_bf16 v[18:33], v[80:83], v[112:115], v[18:33]
	s_waitcnt vmcnt(10)
	v_mfma_f32_32x32x16_bf16 v[18:33], v[84:87], v[116:119], v[18:33]
	s_waitcnt vmcnt(8)
	v_mfma_f32_32x32x16_bf16 v[18:33], v[88:91], v[120:123], v[18:33]
	s_waitcnt vmcnt(6)
	v_mfma_f32_32x32x16_bf16 v[18:33], v[92:95], v[124:127], v[18:33]
	s_waitcnt vmcnt(4)
	v_mfma_f32_32x32x16_bf16 v[18:33], v[96:99], v[128:131], v[18:33]
	s_waitcnt vmcnt(2)
	v_mfma_f32_32x32x16_bf16 v[18:33], v[100:103], v[132:135], v[18:33]
	s_waitcnt vmcnt(0)
	v_mfma_f32_32x32x16_bf16 v[18:33], v[104:107], v[136:139], v[18:33]
	v_mov_b32_e32 v55, 1
	s_nop 11
	v_mov_b32_e32 v36, v18
	v_mov_b32_e32 v52, v18
	v_mov_b32_e32 v53, v19
	v_mov_b32_e32 v54, v19
	v_permlane32_swap_b32_e32 v36, v52
	s_nop 0
	v_permlane32_swap_b32_e32 v53, v54
	v_cndmask_b32_e32 v36, v52, v36, vcc
	v_cndmask_b32_e32 v52, v54, v53, vcc
	v_cndmask_b32_e64 v36, v36, v18, s[0:1]
	v_cndmask_b32_e64 v52, v52, v19, s[0:1]
	v_cndmask_b32_e64 v36, v49, v36, s[18:19]
	s_cselect_b64 s[18:19], -1, 0
	v_cndmask_b32_e64 v52, v49, v52, s[18:19]
	v_cmp_nlg_f32_e64 s[18:19], s49, v36
	s_nop 1
	v_cndmask_b32_e64 v54, v36, v49, s[18:19]
	v_cndmask_b32_e64 v36, 0, -1, s[18:19]
	v_cmp_ngt_f32_e64 s[18:19], v52, v54
	v_mov_b32_e32 v56, v54
	v_mov_b32_e32 v53, v36
	s_and_saveexec_b64 s[20:21], s[18:19]
	s_cbranch_execz .LBB0_1347
	v_cmp_nlg_f32_e64 s[18:19], s49, v52
	v_mov_b32_e32 v53, 1
	s_and_saveexec_b64 s[22:23], s[18:19]
	v_mov_b32_e32 v52, 0xff800000
	v_mov_b32_e32 v53, -1
	s_or_b64 exec, exec, s[22:23]
	v_mov_b32_e32 v56, v52
	v_mov_b32_e32 v52, v54
	v_mov_b32_e32 v55, v36
